# row-pass wave sums: DPP row all-reduce + readlane combine instead of six serialized ds_bpermute round trips per row
# speedup vs baseline: 1.0025x; 1.0017x over previous
.LBB0_604:
	v_ashrrev_i32_e32 v17, 31, v16
	v_lshl_add_u64 v[20:21], v[16:17], 0, v[56:57]
	v_lshlrev_b64 v[18:19], 11, v[16:17]
	v_lshlrev_b64 v[20:21], 9, v[20:21]
	v_lshl_add_u64 v[20:21], v[58:59], 0, v[20:21]
	v_lshl_add_u64 v[22:23], v[62:63], 0, v[18:19]
	global_load_dwordx4 v[74:77], v[22:23], off nt
	global_load_dwordx4 v[78:81], v[20:21], off nt
	v_lshl_add_u64 v[20:21], v[16:17], 0, v[60:61]
	v_lshlrev_b64 v[20:21], 9, v[20:21]
	v_lshl_add_u64 v[20:21], v[58:59], 0, v[20:21]
	global_load_dwordx4 v[82:85], v[20:21], off nt
	global_load_dwordx4 v[86:89], v[22:23], off offset:1024 nt
	v_add_u32_e32 v66, s9, v16
	v_add_u32_e32 v70, s10, v16
	v_add_u32_e32 v68, s11, v16
	v_min_i32_e32 v16, 0x407f, v66
	v_ashrrev_i32_e32 v17, 31, v16
	v_lshl_add_u64 v[26:27], v[16:17], 0, v[56:57]
	v_lshlrev_b64 v[26:27], 9, v[26:27]
	v_lshl_add_u64 v[26:27], v[58:59], 0, v[26:27]
	global_load_dwordx4 v[98:101], v[26:27], off nt
	v_min_i32_e32 v20, 0x407f, v70
	v_min_i32_e32 v24, 0x407f, v68
	v_ashrrev_i32_e32 v21, 31, v20
	v_ashrrev_i32_e32 v25, 31, v24
	v_lshl_add_u64 v[72:73], v[64:65], 0, v[18:19]
	v_lshlrev_b64 v[18:19], 11, v[16:17]
	v_lshl_add_u64 v[16:17], v[16:17], 0, v[60:61]
	v_lshlrev_b64 v[28:29], 11, v[20:21]
	v_lshl_add_u64 v[30:31], v[20:21], 0, v[56:57]
	v_lshl_add_u64 v[20:21], v[20:21], 0, v[60:61]
	v_lshlrev_b64 v[32:33], 11, v[24:25]
	v_lshl_add_u64 v[22:23], v[24:25], 0, v[56:57]
	v_lshl_add_u64 v[24:25], v[24:25], 0, v[60:61]
	v_lshl_add_u64 v[106:107], v[62:63], 0, v[18:19]
	v_lshlrev_b64 v[16:17], 9, v[16:17]
	v_lshlrev_b64 v[18:19], 9, v[30:31]
	v_lshlrev_b64 v[20:21], 9, v[20:21]
	v_lshlrev_b64 v[22:23], 9, v[22:23]
	v_lshlrev_b64 v[24:25], 9, v[24:25]
	v_lshl_add_u64 v[108:109], v[62:63], 0, v[28:29]
	v_lshl_add_u64 v[110:111], v[62:63], 0, v[32:33]
	v_lshl_add_u64 v[112:113], v[58:59], 0, v[16:17]
	v_lshl_add_u64 v[114:115], v[58:59], 0, v[18:19]
	v_lshl_add_u64 v[116:117], v[58:59], 0, v[20:21]
	v_lshl_add_u64 v[118:119], v[58:59], 0, v[22:23]
	v_lshl_add_u64 v[120:121], v[58:59], 0, v[24:25]
	global_load_dwordx4 v[52:55], v[106:107], off nt
	global_load_dwordx4 v[102:105], v[112:113], off nt
	global_load_dwordx4 v[48:51], v[106:107], off offset:1024 nt
	global_load_dwordx4 v[44:47], v[114:115], off nt
	global_load_dwordx4 v[36:39], v[108:109], off nt
	s_waitcnt lgkmcnt(0)
	global_load_dwordx4 v[40:43], v[116:117], off nt
	global_load_dwordx4 v[32:35], v[108:109], off offset:1024 nt
	global_load_dwordx4 v[28:31], v[118:119], off nt
	global_load_dwordx4 v[20:23], v[110:111], off nt
	global_load_dwordx4 v[24:27], v[120:121], off nt
	global_load_dwordx4 v[16:19], v[110:111], off offset:1024 nt
	s_waitcnt vmcnt(15)
	v_lshlrev_b32_e32 v106, 16, v77
	s_waitcnt vmcnt(14)
	v_lshlrev_b32_e32 v114, 16, v78
	v_and_b32_e32 v115, 0xffff0000, v78
	v_lshlrev_b32_e32 v112, 16, v79
	v_and_b32_e32 v113, 0xffff0000, v79
	s_waitcnt vmcnt(13)
	v_lshlrev_b32_e32 v116, 16, v85
	v_and_b32_e32 v117, 0xffff0000, v85
	v_lshlrev_b32_e32 v118, 16, v84
	v_and_b32_e32 v119, 0xffff0000, v84
	v_pk_mul_f32 v[84:85], v[114:115], v[114:115]
	v_lshlrev_b32_e32 v120, 16, v83
	v_and_b32_e32 v121, 0xffff0000, v83
	v_lshlrev_b32_e32 v122, 16, v82
	v_and_b32_e32 v123, 0xffff0000, v82
	v_pk_mul_f32 v[82:83], v[112:113], v[112:113]
	v_add_f32_e32 v67, v84, v85
	v_lshlrev_b32_e32 v110, 16, v80
	v_and_b32_e32 v111, 0xffff0000, v80
	v_add_f32_e32 v67, v82, v67
	v_lshlrev_b32_e32 v108, 16, v81
	v_and_b32_e32 v109, 0xffff0000, v81
	v_pk_mul_f32 v[80:81], v[110:111], v[110:111]
	v_add_f32_e32 v67, v83, v67
	v_add_f32_e32 v67, v80, v67
	v_pk_mul_f32 v[78:79], v[108:109], v[108:109]
	v_add_f32_e32 v67, v81, v67
	v_add_f32_e32 v67, v78, v67
	v_pk_mul_f32 v[130:131], v[122:123], v[122:123]
	v_add_f32_e32 v67, v79, v67
	v_add_f32_e32 v67, v130, v67
	v_pk_mul_f32 v[128:129], v[120:121], v[120:121]
	v_add_f32_e32 v67, v131, v67
	v_add_f32_e32 v67, v128, v67
	v_pk_mul_f32 v[126:127], v[118:119], v[118:119]
	v_add_f32_e32 v67, v129, v67
	v_add_f32_e32 v67, v126, v67
	v_pk_mul_f32 v[124:125], v[116:117], v[116:117]
	v_add_f32_e32 v67, v127, v67
	v_add_f32_e32 v67, v124, v67
	v_add_f32_e32 v67, v125, v67
	s_nop 1
	v_add_f32_dpp v67, v67, v67 quad_perm:[1,0,3,2] row_mask:0xf bank_mask:0xf
	s_nop 1
	v_add_f32_dpp v67, v67, v67 quad_perm:[2,3,0,1] row_mask:0xf bank_mask:0xf
	s_nop 1
	v_add_f32_dpp v67, v67, v67 row_half_mirror row_mask:0xf bank_mask:0xf
	s_nop 1
	v_add_f32_dpp v67, v67, v67 row_mirror row_mask:0xf bank_mask:0xf
	s_nop 0
	v_readlane_b32 s22, v67, 0
	v_readlane_b32 s23, v67, 16
	v_readlane_b32 s24, v67, 32
	v_readlane_b32 s25, v67, 48
	s_nop 1
	v_mov_b32_e32 v67, s22
	v_add_f32_e32 v67, s23, v67
	v_add_f32_e32 v67, s24, v67
	v_add_f32_e32 v67, s25, v67
	v_and_b32_e32 v107, 0xffff0000, v77
	v_lshlrev_b32_e32 v124, 16, v76
	v_and_b32_e32 v125, 0xffff0000, v76
	s_waitcnt vmcnt(11)
	v_lshlrev_b32_e32 v76, 16, v98
	v_and_b32_e32 v77, 0xffff0000, v98
	v_lshlrev_b32_e32 v82, 16, v99
	v_and_b32_e32 v83, 0xffff0000, v99
	v_pk_mul_f32 v[98:99], v[76:77], v[76:77]
	v_lshlrev_b32_e32 v126, 16, v75
	v_and_b32_e32 v127, 0xffff0000, v75
	v_lshlrev_b32_e32 v78, 16, v74
	v_and_b32_e32 v79, 0xffff0000, v74
	v_lshlrev_b32_e32 v74, 16, v100
	v_and_b32_e32 v75, 0xffff0000, v100
	v_lshlrev_b32_e32 v80, 16, v101
	v_and_b32_e32 v81, 0xffff0000, v101
	v_pk_mul_f32 v[100:101], v[82:83], v[82:83]
	v_pk_mul_f32 v[136:137], v[74:75], v[74:75]
	v_pk_mul_f32 v[138:139], v[80:81], v[80:81]
	v_lshlrev_b32_e32 v128, 16, v89
	v_and_b32_e32 v129, 0xffff0000, v89
	v_lshlrev_b32_e32 v130, 16, v88
	v_and_b32_e32 v131, 0xffff0000, v88
	s_waitcnt vmcnt(9)
	v_lshlrev_b32_e32 v88, 16, v102
	v_fmamk_f32 v67, v67, 0x3a800000, v96
	v_mul_f32_e32 v69, 0x4b800000, v67
	v_cmp_gt_f32_e32 vcc, s13, v67
	v_and_b32_e32 v89, 0xffff0000, v102
	v_pk_mul_f32 v[142:143], v[88:89], v[88:89]
	v_cndmask_b32_e32 v67, v67, v69, vcc
	v_rsq_f32_e32 v67, v67
	v_lshlrev_b32_e32 v132, 16, v87
	v_and_b32_e32 v133, 0xffff0000, v87
	v_lshlrev_b32_e32 v134, 16, v86
	v_mul_f32_e32 v69, 0x45800000, v67
	v_cndmask_b32_e32 v140, v67, v69, vcc
	v_add_f32_e32 v67, v98, v99
	v_add_f32_e32 v67, v100, v67
	v_add_f32_e32 v67, v101, v67
	v_add_f32_e32 v67, v136, v67
	v_add_f32_e32 v67, v137, v67
	v_add_f32_e32 v67, v138, v67
	v_add_f32_e32 v67, v139, v67
	v_and_b32_e32 v135, 0xffff0000, v86
	v_lshlrev_b32_e32 v86, 16, v103
	v_and_b32_e32 v87, 0xffff0000, v103
	v_add_f32_e32 v67, v142, v67
	v_pk_mul_f32 v[84:85], v[140:141], v[114:115] op_sel_hi:[0,1]
	v_pk_mul_f32 v[102:103], v[86:87], v[86:87]
	v_add_f32_e32 v67, v143, v67
	v_pk_fma_f32 v[114:115], v[4:5], v[84:85], v[78:79]
	v_lshlrev_b32_e32 v84, 16, v104
	v_and_b32_e32 v85, 0xffff0000, v104
	v_add_f32_e32 v67, v102, v67
	v_pk_mul_f32 v[144:145], v[84:85], v[84:85]
	v_add_f32_e32 v67, v103, v67
	v_lshlrev_b32_e32 v78, 16, v105
	v_and_b32_e32 v79, 0xffff0000, v105
	v_add_f32_e32 v67, v144, v67
	v_pk_mul_f32 v[104:105], v[78:79], v[78:79]
	v_add_f32_e32 v67, v145, v67
	v_add_f32_e32 v67, v104, v67
	v_add_f32_e32 v67, v105, v67
	s_nop 1
	v_add_f32_dpp v67, v67, v67 quad_perm:[1,0,3,2] row_mask:0xf bank_mask:0xf
	s_nop 1
	v_add_f32_dpp v67, v67, v67 quad_perm:[2,3,0,1] row_mask:0xf bank_mask:0xf
	s_nop 1
	v_add_f32_dpp v67, v67, v67 row_half_mirror row_mask:0xf bank_mask:0xf
	s_nop 1
	v_add_f32_dpp v67, v67, v67 row_mirror row_mask:0xf bank_mask:0xf
	s_nop 0
	v_readlane_b32 s22, v67, 0
	v_readlane_b32 s23, v67, 16
	v_readlane_b32 s24, v67, 32
	v_readlane_b32 s25, v67, 48
	s_nop 1
	v_mov_b32_e32 v67, s22
	v_add_f32_e32 v67, s23, v67
	v_add_f32_e32 v67, s24, v67
	v_add_f32_e32 v67, s25, v67
	v_pk_mul_f32 v[98:99], v[140:141], v[110:111] op_sel_hi:[0,1]
	v_pk_mul_f32 v[112:113], v[140:141], v[112:113] op_sel_hi:[0,1]
	v_pk_fma_f32 v[102:103], v[0:1], v[98:99], v[124:125]
	v_pk_mul_f32 v[98:99], v[140:141], v[108:109] op_sel_hi:[0,1]
	v_pk_fma_f32 v[100:101], v[6:7], v[112:113], v[126:127]
	v_pk_fma_f32 v[104:105], v[2:3], v[98:99], v[106:107]
	v_cvt_pk_bf16_f32 v98, v114, v115
	v_cvt_pk_bf16_f32 v99, v100, v101
	v_cvt_pk_bf16_f32 v100, v102, v103
	v_cvt_pk_bf16_f32 v101, v104, v105
	global_store_dwordx4 v[72:73], v[98:101], off
	s_nop 0
	v_pk_mul_f32 v[102:103], v[140:141], v[118:119] op_sel_hi:[0,1]
	v_pk_mul_f32 v[98:99], v[140:141], v[122:123] op_sel_hi:[0,1]
	v_pk_mul_f32 v[100:101], v[140:141], v[120:121] op_sel_hi:[0,1]
	v_pk_mul_f32 v[104:105], v[140:141], v[116:117] op_sel_hi:[0,1]
	v_pk_fma_f32 v[98:99], v[12:13], v[98:99], v[134:135]
	v_pk_fma_f32 v[100:101], v[14:15], v[100:101], v[132:133]
	v_pk_fma_f32 v[102:103], v[8:9], v[102:103], v[130:131]
	v_pk_fma_f32 v[104:105], v[10:11], v[104:105], v[128:129]
	v_cvt_pk_bf16_f32 v98, v98, v99
	v_cvt_pk_bf16_f32 v99, v100, v101
	v_cvt_pk_bf16_f32 v100, v102, v103
	v_cvt_pk_bf16_f32 v101, v104, v105
	v_cmp_gt_i32_e32 vcc, s8, v66
	global_store_dwordx4 v[72:73], v[98:101], off offset:1024
	s_and_saveexec_b64 s[6:7], vcc
	s_cbranch_execz .LBB0_606
	v_fmamk_f32 v67, v67, 0x3a800000, v96
	v_mul_f32_e32 v69, 0x4b800000, v67
	v_cmp_gt_f32_e32 vcc, s13, v67
	v_lshlrev_b32_e32 v100, 16, v52
	v_and_b32_e32 v101, 0xffff0000, v52
	v_cndmask_b32_e32 v67, v67, v69, vcc
	v_rsq_f32_e32 v69, v67
	v_ashrrev_i32_e32 v67, 31, v66
	v_lshlrev_b64 v[72:73], 11, v[66:67]
	v_lshlrev_b32_e32 v52, 16, v53
	v_mul_f32_e32 v67, 0x45800000, v69
	v_cndmask_b32_e32 v98, v69, v67, vcc
	v_and_b32_e32 v53, 0xffff0000, v53
	v_pk_mul_f32 v[82:83], v[98:99], v[82:83] op_sel_hi:[0,1]
	v_pk_fma_f32 v[82:83], v[6:7], v[82:83], v[52:53]
	v_lshlrev_b32_e32 v52, 16, v54
	v_and_b32_e32 v53, 0xffff0000, v54
	v_pk_mul_f32 v[74:75], v[98:99], v[74:75] op_sel_hi:[0,1]
	v_pk_mul_f32 v[76:77], v[98:99], v[76:77] op_sel_hi:[0,1]
	v_pk_fma_f32 v[74:75], v[0:1], v[74:75], v[52:53]
	v_lshlrev_b32_e32 v52, 16, v55
	v_and_b32_e32 v53, 0xffff0000, v55
	v_pk_mul_f32 v[54:55], v[98:99], v[80:81] op_sel_hi:[0,1]
	v_pk_fma_f32 v[76:77], v[4:5], v[76:77], v[100:101]
	v_pk_fma_f32 v[80:81], v[2:3], v[54:55], v[52:53]
	v_cvt_pk_bf16_f32 v52, v76, v77
	v_cvt_pk_bf16_f32 v53, v82, v83
	v_cvt_pk_bf16_f32 v54, v74, v75
	v_cvt_pk_bf16_f32 v55, v80, v81
	v_lshl_add_u64 v[72:73], v[64:65], 0, v[72:73]
	global_store_dwordx4 v[72:73], v[52:55], off
	v_pk_mul_f32 v[74:75], v[98:99], v[84:85] op_sel_hi:[0,1]
	s_waitcnt vmcnt(11)
	v_lshlrev_b32_e32 v52, 16, v48
	v_and_b32_e32 v53, 0xffff0000, v48
	v_pk_mul_f32 v[54:55], v[98:99], v[88:89] op_sel_hi:[0,1]
	v_pk_fma_f32 v[52:53], v[12:13], v[54:55], v[52:53]
	v_lshlrev_b32_e32 v48, 16, v49
	v_and_b32_e32 v49, 0xffff0000, v49
	v_pk_mul_f32 v[54:55], v[98:99], v[86:87] op_sel_hi:[0,1]
	v_pk_fma_f32 v[54:55], v[14:15], v[54:55], v[48:49]
	v_lshlrev_b32_e32 v48, 16, v50
	v_and_b32_e32 v49, 0xffff0000, v50
	v_pk_fma_f32 v[74:75], v[8:9], v[74:75], v[48:49]
	v_lshlrev_b32_e32 v48, 16, v51
	v_and_b32_e32 v49, 0xffff0000, v51
	v_pk_mul_f32 v[50:51], v[98:99], v[78:79] op_sel_hi:[0,1]
	v_pk_fma_f32 v[76:77], v[10:11], v[50:51], v[48:49]
	v_cvt_pk_bf16_f32 v48, v52, v53
	v_cvt_pk_bf16_f32 v49, v54, v55
	v_cvt_pk_bf16_f32 v50, v74, v75
	v_cvt_pk_bf16_f32 v51, v76, v77
	global_store_dwordx4 v[72:73], v[48:51], off offset:1024
.LBB0_606:
	s_or_b64 exec, exec, s[6:7]
	s_waitcnt vmcnt(9)
	v_lshlrev_b32_e32 v48, 16, v44
	v_and_b32_e32 v49, 0xffff0000, v44
	v_pk_mul_f32 v[72:73], v[48:49], v[48:49]
	v_lshlrev_b32_e32 v50, 16, v45
	v_and_b32_e32 v51, 0xffff0000, v45
	v_pk_mul_f32 v[74:75], v[50:51], v[50:51]
	v_add_f32_e32 v67, v72, v73
	v_lshlrev_b32_e32 v52, 16, v46
	v_and_b32_e32 v53, 0xffff0000, v46
	v_add_f32_e32 v67, v74, v67
	v_pk_mul_f32 v[76:77], v[52:53], v[52:53]
	v_add_f32_e32 v67, v75, v67
	v_lshlrev_b32_e32 v54, 16, v47
	v_and_b32_e32 v55, 0xffff0000, v47
	v_add_f32_e32 v67, v76, v67
	v_pk_mul_f32 v[78:79], v[54:55], v[54:55]
	v_add_f32_e32 v67, v77, v67
	s_waitcnt vmcnt(7)
	v_lshlrev_b32_e32 v44, 16, v40
	v_and_b32_e32 v45, 0xffff0000, v40
	v_add_f32_e32 v67, v78, v67
	v_pk_mul_f32 v[80:81], v[44:45], v[44:45]
	v_add_f32_e32 v67, v79, v67
	v_lshlrev_b32_e32 v40, 16, v41
	v_and_b32_e32 v41, 0xffff0000, v41
	v_add_f32_e32 v67, v80, v67
	v_pk_mul_f32 v[82:83], v[40:41], v[40:41]
	v_add_f32_e32 v67, v81, v67
	v_lshlrev_b32_e32 v46, 16, v42
	v_and_b32_e32 v47, 0xffff0000, v42
	v_add_f32_e32 v67, v82, v67
	v_pk_mul_f32 v[84:85], v[46:47], v[46:47]
	v_add_f32_e32 v67, v83, v67
	v_lshlrev_b32_e32 v42, 16, v43
	v_and_b32_e32 v43, 0xffff0000, v43
	v_add_f32_e32 v67, v84, v67
	v_pk_mul_f32 v[86:87], v[42:43], v[42:43]
	v_add_f32_e32 v67, v85, v67
	v_add_f32_e32 v67, v86, v67
	v_add_f32_e32 v67, v87, v67
	s_waitcnt lgkmcnt(0)
	s_nop 1
	v_add_f32_dpp v67, v67, v67 quad_perm:[1,0,3,2] row_mask:0xf bank_mask:0xf
	s_nop 1
	v_add_f32_dpp v67, v67, v67 quad_perm:[2,3,0,1] row_mask:0xf bank_mask:0xf
	s_nop 1
	v_add_f32_dpp v67, v67, v67 row_half_mirror row_mask:0xf bank_mask:0xf
	s_nop 1
	v_add_f32_dpp v67, v67, v67 row_mirror row_mask:0xf bank_mask:0xf
	s_nop 0
	v_readlane_b32 s22, v67, 0
	v_readlane_b32 s23, v67, 16
	v_readlane_b32 s24, v67, 32
	v_readlane_b32 s25, v67, 48
	s_nop 1
	v_mov_b32_e32 v67, s22
	v_add_f32_e32 v67, s23, v67
	v_add_f32_e32 v67, s24, v67
	v_add_f32_e32 v67, s25, v67
	v_cmp_gt_i32_e32 vcc, s8, v70
	s_and_saveexec_b64 s[6:7], vcc
	s_cbranch_execz .LBB0_608
	s_waitcnt vmcnt(6)
	v_lshlrev_b32_e32 v76, 16, v32
	v_and_b32_e32 v77, 0xffff0000, v32
	v_mov_b32_e32 v32, v67
	v_fmamk_f32 v32, v32, 0x3a800000, v96
	v_lshlrev_b32_e32 v78, 16, v33
	v_and_b32_e32 v79, 0xffff0000, v33
	v_mul_f32_e32 v33, 0x4b800000, v32
	v_cmp_gt_f32_e32 vcc, s13, v32
	v_lshlrev_b32_e32 v72, 16, v36
	v_and_b32_e32 v73, 0xffff0000, v36
	v_cndmask_b32_e32 v32, v32, v33, vcc
	v_rsq_f32_e32 v32, v32
	v_lshlrev_b32_e32 v36, 16, v37
	v_and_b32_e32 v37, 0xffff0000, v37
	v_lshlrev_b32_e32 v80, 16, v34
	v_mul_f32_e32 v33, 0x45800000, v32
	v_cndmask_b32_e32 v84, v32, v33, vcc
	v_and_b32_e32 v81, 0xffff0000, v34
	v_lshlrev_b32_e32 v82, 16, v35
	v_and_b32_e32 v83, 0xffff0000, v35
	v_pk_mul_f32 v[34:35], v[84:85], v[50:51] op_sel_hi:[0,1]
	v_lshlrev_b32_e32 v74, 16, v38
	v_and_b32_e32 v75, 0xffff0000, v38
	v_lshlrev_b32_e32 v38, 16, v39
	v_and_b32_e32 v39, 0xffff0000, v39
	v_ashrrev_i32_e32 v71, 31, v70
	v_pk_mul_f32 v[32:33], v[84:85], v[48:49] op_sel_hi:[0,1]
	v_pk_fma_f32 v[34:35], v[6:7], v[34:35], v[36:37]
	v_pk_mul_f32 v[36:37], v[84:85], v[52:53] op_sel_hi:[0,1]
	v_pk_mul_f32 v[48:49], v[84:85], v[54:55] op_sel_hi:[0,1]
	v_lshlrev_b64 v[70:71], 11, v[70:71]
	v_pk_fma_f32 v[32:33], v[4:5], v[32:33], v[72:73]
	v_pk_fma_f32 v[36:37], v[0:1], v[36:37], v[74:75]
	v_pk_fma_f32 v[38:39], v[2:3], v[48:49], v[38:39]
	v_cvt_pk_bf16_f32 v32, v32, v33
	v_cvt_pk_bf16_f32 v33, v34, v35
	v_cvt_pk_bf16_f32 v34, v36, v37
	v_cvt_pk_bf16_f32 v35, v38, v39
	v_lshl_add_u64 v[36:37], v[64:65], 0, v[70:71]
	global_store_dwordx4 v[36:37], v[32:35], off
	v_pk_mul_f32 v[38:39], v[84:85], v[46:47] op_sel_hi:[0,1]
	v_pk_fma_f32 v[38:39], v[8:9], v[38:39], v[80:81]
	v_pk_mul_f32 v[32:33], v[84:85], v[44:45] op_sel_hi:[0,1]
	v_pk_mul_f32 v[34:35], v[84:85], v[40:41] op_sel_hi:[0,1]
	v_pk_mul_f32 v[40:41], v[84:85], v[42:43] op_sel_hi:[0,1]
	v_pk_fma_f32 v[32:33], v[12:13], v[32:33], v[76:77]
	v_pk_fma_f32 v[34:35], v[14:15], v[34:35], v[78:79]
	v_pk_fma_f32 v[40:41], v[10:11], v[40:41], v[82:83]
	v_cvt_pk_bf16_f32 v32, v32, v33
	v_cvt_pk_bf16_f32 v33, v34, v35
	v_cvt_pk_bf16_f32 v34, v38, v39
	v_cvt_pk_bf16_f32 v35, v40, v41
	global_store_dwordx4 v[36:37], v[32:35], off offset:1024
.LBB0_608:
	s_or_b64 exec, exec, s[6:7]
	s_waitcnt vmcnt(5)
	v_lshlrev_b32_e32 v32, 16, v28
	v_and_b32_e32 v33, 0xffff0000, v28
	v_pk_mul_f32 v[40:41], v[32:33], v[32:33]
	v_lshlrev_b32_e32 v34, 16, v29
	v_and_b32_e32 v35, 0xffff0000, v29
	v_pk_mul_f32 v[42:43], v[34:35], v[34:35]
	v_add_f32_e32 v40, v40, v41
	v_lshlrev_b32_e32 v36, 16, v30
	v_and_b32_e32 v37, 0xffff0000, v30
	v_add_f32_e32 v40, v42, v40
	v_pk_mul_f32 v[44:45], v[36:37], v[36:37]
	v_add_f32_e32 v40, v43, v40
	v_lshlrev_b32_e32 v38, 16, v31
	v_and_b32_e32 v39, 0xffff0000, v31
	v_add_f32_e32 v40, v44, v40
	v_pk_mul_f32 v[46:47], v[38:39], v[38:39]
	v_add_f32_e32 v40, v45, v40
	s_waitcnt vmcnt(3)
	v_lshlrev_b32_e32 v28, 16, v24
	v_and_b32_e32 v29, 0xffff0000, v24
	v_add_f32_e32 v40, v46, v40
	v_pk_mul_f32 v[48:49], v[28:29], v[28:29]
	v_add_f32_e32 v40, v47, v40
	v_lshlrev_b32_e32 v24, 16, v25
	v_and_b32_e32 v25, 0xffff0000, v25
	v_add_f32_e32 v40, v48, v40
	v_pk_mul_f32 v[50:51], v[24:25], v[24:25]
	v_add_f32_e32 v40, v49, v40
	v_lshlrev_b32_e32 v30, 16, v26
	v_and_b32_e32 v31, 0xffff0000, v26
	v_add_f32_e32 v40, v50, v40
	v_pk_mul_f32 v[52:53], v[30:31], v[30:31]
	v_add_f32_e32 v40, v51, v40
	v_lshlrev_b32_e32 v26, 16, v27
	v_and_b32_e32 v27, 0xffff0000, v27
	v_add_f32_e32 v40, v52, v40
	v_pk_mul_f32 v[54:55], v[26:27], v[26:27]
	v_add_f32_e32 v40, v53, v40
	v_add_f32_e32 v40, v54, v40
	v_add_f32_e32 v40, v55, v40
	s_nop 1
	v_add_f32_dpp v40, v40, v40 quad_perm:[1,0,3,2] row_mask:0xf bank_mask:0xf
	s_nop 1
	v_add_f32_dpp v40, v40, v40 quad_perm:[2,3,0,1] row_mask:0xf bank_mask:0xf
	s_nop 1
	v_add_f32_dpp v40, v40, v40 row_half_mirror row_mask:0xf bank_mask:0xf
	s_nop 1
	v_add_f32_dpp v40, v40, v40 row_mirror row_mask:0xf bank_mask:0xf
	s_nop 0
	v_readlane_b32 s22, v40, 0
	v_readlane_b32 s23, v40, 16
	v_readlane_b32 s24, v40, 32
	v_readlane_b32 s25, v40, 48
	s_nop 1
	v_mov_b32_e32 v40, s22
	v_add_f32_e32 v40, s23, v40
	v_add_f32_e32 v40, s24, v40
	v_add_f32_e32 v40, s25, v40
	v_cmp_gt_i32_e32 vcc, s8, v68
	s_and_saveexec_b64 s[6:7], vcc
	s_cbranch_execz .LBB0_603
	s_waitcnt vmcnt(2)
	v_lshlrev_b32_e32 v46, 16, v16
	v_and_b32_e32 v47, 0xffff0000, v16
	v_mov_b32_e32 v16, v40
	v_fmamk_f32 v16, v16, 0x3a800000, v96
	v_lshlrev_b32_e32 v48, 16, v17
	v_and_b32_e32 v49, 0xffff0000, v17
	v_mul_f32_e32 v17, 0x4b800000, v16
	v_cmp_gt_f32_e32 vcc, s13, v16
	v_lshlrev_b32_e32 v42, 16, v20
	v_and_b32_e32 v43, 0xffff0000, v20
	v_cndmask_b32_e32 v16, v16, v17, vcc
	v_rsq_f32_e32 v16, v16
	v_lshlrev_b32_e32 v20, 16, v21
	v_and_b32_e32 v21, 0xffff0000, v21
	v_lshlrev_b32_e32 v50, 16, v18
	v_mul_f32_e32 v17, 0x45800000, v16
	v_cndmask_b32_e32 v52, v16, v17, vcc
	v_and_b32_e32 v51, 0xffff0000, v18
	v_lshlrev_b32_e32 v40, 16, v19
	v_and_b32_e32 v41, 0xffff0000, v19
	v_pk_mul_f32 v[18:19], v[52:53], v[34:35] op_sel_hi:[0,1]
	v_lshlrev_b32_e32 v44, 16, v22
	v_and_b32_e32 v45, 0xffff0000, v22
	v_lshlrev_b32_e32 v22, 16, v23
	v_and_b32_e32 v23, 0xffff0000, v23
	v_ashrrev_i32_e32 v69, 31, v68
	v_pk_mul_f32 v[16:17], v[52:53], v[32:33] op_sel_hi:[0,1]
	v_pk_fma_f32 v[18:19], v[6:7], v[18:19], v[20:21]
	v_pk_mul_f32 v[20:21], v[52:53], v[36:37] op_sel_hi:[0,1]
	v_pk_mul_f32 v[32:33], v[52:53], v[38:39] op_sel_hi:[0,1]
	v_lshlrev_b64 v[54:55], 11, v[68:69]
	v_pk_fma_f32 v[16:17], v[4:5], v[16:17], v[42:43]
	v_pk_fma_f32 v[20:21], v[0:1], v[20:21], v[44:45]
	v_pk_fma_f32 v[22:23], v[2:3], v[32:33], v[22:23]
	v_cvt_pk_bf16_f32 v16, v16, v17
	v_cvt_pk_bf16_f32 v17, v18, v19
	v_cvt_pk_bf16_f32 v18, v20, v21
	v_cvt_pk_bf16_f32 v19, v22, v23
	v_lshl_add_u64 v[20:21], v[64:65], 0, v[54:55]
	global_store_dwordx4 v[20:21], v[16:19], off
	v_pk_mul_f32 v[22:23], v[52:53], v[30:31] op_sel_hi:[0,1]
	v_pk_fma_f32 v[22:23], v[8:9], v[22:23], v[50:51]
	v_pk_mul_f32 v[16:17], v[52:53], v[28:29] op_sel_hi:[0,1]
	v_pk_mul_f32 v[18:19], v[52:53], v[24:25] op_sel_hi:[0,1]
	v_pk_mul_f32 v[24:25], v[52:53], v[26:27] op_sel_hi:[0,1]
	v_pk_fma_f32 v[16:17], v[12:13], v[16:17], v[46:47]
	v_pk_fma_f32 v[18:19], v[14:15], v[18:19], v[48:49]
	v_pk_fma_f32 v[24:25], v[10:11], v[24:25], v[40:41]
	v_cvt_pk_bf16_f32 v16, v16, v17
	v_cvt_pk_bf16_f32 v17, v18, v19
	v_cvt_pk_bf16_f32 v18, v22, v23
	v_cvt_pk_bf16_f32 v19, v24, v25
	global_store_dwordx4 v[20:21], v[16:19], off offset:1024
	s_branch .LBB0_603
